# v46 + MLA attention KV loop: next-tile global loads issued earlier (as staging registers free up) in both half-steps
# baseline (speedup 1.0000x reference)
; #define PK4(P, B_, OUT) do { const u32x4 w = {cvtpk(P[B_+0], P[B_+1]), cvtpk(P[B_+2], P[B_+3]), cvtpk(P[B_+4], P[B_+5]), cvtpk(P[B_+6], P[B_+7])};     \
;         OUT = *reinterpret_cast<const bf16x8*>(&w); } while (0)
; __device__ __forceinline__ void finishSM(f32x16& p0, f32x16& p1, float alpha, float& l_reg, bf16x8& pa0, bf16x8& pa1, bf16x8& pa2, bf16x8& pa3) {
;     for (int r = 0; r < 16; ++r) p1[r] = __builtin_amdgcn_exp2f(p1[r]);
;     float ps = 0; for (int r = 0; r < 16; ++r) ps += p0[r]; for (int r = 0; r < 16; ++r) ps += p1[r];
;     { auto rr = __builtin_amdgcn_permlane32_swap(__float_as_uint(ps), __float_as_uint(ps), false, false);
;       ps = __uint_as_float(rr[0]) + __uint_as_float(rr[1]); }
;     l_reg = l_reg * alpha + ps;
;     ...
;     PK4(p0, 0, pa0); PK4(p0, 8, pa1); PK4(p1, 0, pa2); PK4(p1, 8, pa3);
;     ...
; }
; template <int KB, bool SK, bool PE>
; __device__ __forceinline__ void qkt(f32x16& p0, f32x16& p1, const char* lds, int r32, int hi, int wid, int lane, const bf16x8* qr, bool act) {
;     if (SK && !act) { const float NEG = -__builtin_inff();
; #pragma unroll
;         for (int r = 0; r < 16; ++r) { p0[r] = NEG; p1[r] = NEG; } return; }
;     p0 = f32x16{}; p1 = f32x16{};
;     const char* kb[4];
; #pragma unroll
;     for (int dd = 0; dd < 4; ++dd) kb[dd] = lds + OFF_K + KB * SHM_K + KSWZ(r32, (dd * 16 + hi * 8) * 2);
; #pragma unroll
;     for (int d0 = 0; d0 < 8; ++d0) { const char* a = kb[d0 & 3] + (d0 >> 2) * 128;
;         bf16x8 b0 = *reinterpret_cast<const bf16x8*>(a);
;         bf16x8 b1 = *reinterpret_cast<const bf16x8*>(a + 32 * 256);
;         p0 = __builtin_amdgcn_mfma_f32_32x32x16_bf16(b0, qr[d0], p0, 0, 0, 0);
;         p1 = __builtin_amdgcn_mfma_f32_32x32x16_bf16(b1, qr[d0], p1, 0, 0, 0); }
;     if constexpr (PE) {
;         const char* kp = lds + OFF_KPE + KB * SHM_KPE + r32 * KPE_ROW + hi * 16;
;         const char* qp = lds + OFF_QPE + wid * 4096 + lane * 16;
; #pragma unroll
;         for (int d0 = 0; d0 < 4; ++d0) {
;             bf16x8 b0 = *reinterpret_cast<const bf16x8*>(kp + d0 * 32);
;             bf16x8 b1 = *reinterpret_cast<const bf16x8*>(kp + d0 * 32 + 32 * KPE_ROW);
;             bf16x8 qf = *reinterpret_cast<const bf16x8*>(qp + d0 * 1024);
;             p0 = __builtin_amdgcn_mfma_f32_32x32x16_bf16(b0, qf, p0, 0, 0, 0);
;             p1 = __builtin_amdgcn_mfma_f32_32x32x16_bf16(b1, qf, p1, 0, 0, 0); }
;     }
.LBB0_370:
	ds_read_b128 v[68:71], v222 offset:49152
	ds_read_b128 v[72:75], v222 offset:57344
	ds_read_b128 v[100:103], v221 offset:49152
	ds_read_b128 v[104:107], v221 offset:57344
	v_exp_f32_e32 v116, v176
	v_exp_f32_e32 v117, v177
	s_waitcnt lgkmcnt(3)
	v_mfma_f32_32x32x16_bf16 v[84:99], v[68:71], v[160:163], 0
	v_exp_f32_e32 v118, v174
	v_exp_f32_e32 v119, v175
	v_exp_f32_e32 v120, v172
	v_exp_f32_e32 v121, v173
	v_exp_f32_e32 v122, v170
	v_exp_f32_e32 v123, v171
	v_exp_f32_e32 v124, v168
	s_waitcnt lgkmcnt(2)
	v_mfma_f32_32x32x16_bf16 v[68:83], v[72:75], v[160:163], 0
	v_exp_f32_e32 v125, v169
	s_sub_i32 s44, s42, 63
	s_lshl_b64 s[6:7], s[44:45], 8
	s_add_u32 s54, s86, s6
	s_addc_u32 s55, s87, s7
	s_add_u32 s6, s88, s6
	s_addc_u32 s7, s89, s7
	v_lshl_add_u64 v[164:165], s[6:7], 0, v[200:201]
	v_lshl_add_u64 v[172:173], s[54:55], 0, v[200:201]
	v_add_co_u32_e32 v168, vcc, s43, v164
	s_lshl_b64 s[6:7], s[44:45], 7
	s_nop 0
	v_addc_co_u32_e32 v169, vcc, 0, v165, vcc
	global_load_dwordx4 v[164:167], v[164:165], off
	s_nop 0
	global_load_dwordx4 v[168:171], v[168:169], off
	s_nop 0
	global_load_dwordx4 v[172:175], v[172:173], off
	s_add_i32 s4, s42, 0xffffff81
	s_sub_i32 s5, s42, 64
	s_waitcnt lgkmcnt(1)
	v_mfma_f32_32x32x16_bf16 v[84:99], v[100:103], v[156:159], v[84:99]
	s_waitcnt lgkmcnt(0)
	v_mfma_f32_32x32x16_bf16 v[68:83], v[104:107], v[156:159], v[68:83]
	ds_read_b128 v[100:103], v220 offset:49152
	ds_read_b128 v[104:107], v220 offset:57344
	s_waitcnt lgkmcnt(1)
	v_mfma_f32_32x32x16_bf16 v[84:99], v[100:103], v[152:155], v[84:99]
	s_waitcnt lgkmcnt(0)
	v_mfma_f32_32x32x16_bf16 v[68:83], v[104:107], v[152:155], v[68:83]
	ds_read_b128 v[100:103], v219 offset:49152
	ds_read_b128 v[104:107], v219 offset:57344
	s_waitcnt lgkmcnt(1)
	v_mfma_f32_32x32x16_bf16 v[84:99], v[100:103], v[148:151], v[84:99]
	s_waitcnt lgkmcnt(0)
	v_mfma_f32_32x32x16_bf16 v[68:83], v[104:107], v[148:151], v[68:83]
	ds_read_b128 v[100:103], v222 offset:49280
	ds_read_b128 v[104:107], v222 offset:57472
	s_waitcnt lgkmcnt(1)
	v_mfma_f32_32x32x16_bf16 v[84:99], v[100:103], v[144:147], v[84:99]
	s_waitcnt lgkmcnt(0)
	v_mfma_f32_32x32x16_bf16 v[68:83], v[104:107], v[144:147], v[68:83]
	ds_read_b128 v[100:103], v221 offset:49280
	ds_read_b128 v[104:107], v221 offset:57472
	s_waitcnt lgkmcnt(1)
	v_mfma_f32_32x32x16_bf16 v[84:99], v[100:103], v[140:143], v[84:99]
	s_waitcnt lgkmcnt(0)
	v_mfma_f32_32x32x16_bf16 v[68:83], v[104:107], v[140:143], v[68:83]
	ds_read_b128 v[100:103], v220 offset:49280
	ds_read_b128 v[104:107], v220 offset:57472
	s_waitcnt lgkmcnt(1)
	v_mfma_f32_32x32x16_bf16 v[84:99], v[100:103], v[136:139], v[84:99]
	s_waitcnt lgkmcnt(0)
	v_mfma_f32_32x32x16_bf16 v[68:83], v[104:107], v[136:139], v[68:83]
	ds_read_b128 v[100:103], v219 offset:49280
	ds_read_b128 v[104:107], v219 offset:57472
	s_waitcnt lgkmcnt(1)
	v_mfma_f32_32x32x16_bf16 v[84:99], v[100:103], v[132:135], v[84:99]
	s_waitcnt lgkmcnt(0)
	v_mfma_f32_32x32x16_bf16 v[68:83], v[104:107], v[132:135], v[68:83]
	ds_read_b128 v[100:103], v233 offset:4608
	ds_read_b128 v[104:107], v215
	ds_read_b128 v[108:111], v233
	ds_read_b128 v[112:115], v233 offset:32
	s_waitcnt lgkmcnt(1)
	v_mfma_f32_32x32x16_bf16 v[84:99], v[108:111], v[104:107], v[84:99]
	v_mfma_f32_32x32x16_bf16 v[68:83], v[100:103], v[104:107], v[68:83]
	ds_read_b128 v[100:103], v233 offset:4640
	ds_read_b128 v[104:107], v215 offset:1024
	s_waitcnt lgkmcnt(0)
	v_mfma_f32_32x32x16_bf16 v[84:99], v[112:115], v[104:107], v[84:99]
	v_exp_f32_e32 v112, v180
	v_exp_f32_e32 v113, v181
	v_exp_f32_e32 v114, v178
	v_exp_f32_e32 v115, v179
	v_lshl_add_u64 v[176:177], s[54:55], 0, v[200:201]
	s_nop 0
	v_add_co_u32_e32 v176, vcc, s43, v176
	s_nop 1
	v_addc_co_u32_e32 v177, vcc, 0, v177, vcc
	s_nop 0
	global_load_dwordx4 v[176:179], v[176:177], off
	v_mfma_f32_32x32x16_bf16 v[68:83], v[100:103], v[104:107], v[68:83]
	ds_read_b128 v[100:103], v233 offset:64
	ds_read_b128 v[104:107], v233 offset:4672
	ds_read_b128 v[108:111], v215 offset:2048
	s_waitcnt lgkmcnt(0)
	v_mfma_f32_32x32x16_bf16 v[84:99], v[100:103], v[108:111], v[84:99]
	v_mfma_f32_32x32x16_bf16 v[68:83], v[104:107], v[108:111], v[68:83]
	ds_read_b128 v[100:103], v233 offset:96
	ds_read_b128 v[104:107], v233 offset:4704
	ds_read_b128 v[108:111], v215 offset:3072
	s_waitcnt lgkmcnt(0)
	v_mfma_f32_32x32x16_bf16 v[84:99], v[100:103], v[108:111], v[84:99]
	v_add_f32_e32 v100, 0, v236
	v_add_f32_e32 v100, v237, v100
	v_add_f32_e32 v100, v199, v100
	v_add_f32_e32 v100, v235, v100
	v_add_f32_e32 v100, v197, v100
	v_add_f32_e32 v100, v214, v100
	v_add_f32_e32 v100, v196, v100
	v_add_f32_e32 v100, v198, v100
	v_add_f32_e32 v100, v193, v100
	v_add_f32_e32 v100, v195, v100
	v_add_f32_e32 v100, v191, v100
	v_add_f32_e32 v100, v194, v100
	v_mfma_f32_32x32x16_bf16 v[68:83], v[104:107], v[108:111], v[68:83]
	v_exp_f32_e32 v110, v182
	v_add_f32_e32 v100, v188, v100
	v_exp_f32_e32 v111, v183
	v_add_f32_e32 v100, v192, v100
	v_add_f32_e32 v100, v187, v100
	v_add_f32_e32 v100, v189, v100
	v_add_f32_e32 v100, v110, v100
	v_add_f32_e32 v100, v111, v100
	v_add_f32_e32 v100, v112, v100
	v_add_f32_e32 v100, v113, v100
	v_add_f32_e32 v100, v114, v100
	v_add_f32_e32 v100, v115, v100
	v_add_f32_e32 v100, v116, v100
	v_add_f32_e32 v100, v117, v100
	v_add_f32_e32 v100, v118, v100
	v_add_f32_e32 v100, v119, v100
	v_add_f32_e32 v100, v120, v100
	v_add_f32_e32 v100, v121, v100
	v_add_f32_e32 v100, v122, v100
	v_add_f32_e32 v100, v123, v100
	v_add_f32_e32 v100, v124, v100
	v_add_f32_e32 v104, v125, v100
	v_mov_b32_e32 v105, v104
	s_nop 1
	v_permlane32_swap_b32_e32 v104, v105
	v_cvt_pk_bf16_f32 v100, v236, v237
	v_cvt_pk_bf16_f32 v101, v199, v235
	v_cvt_pk_bf16_f32 v102, v197, v214
	v_cvt_pk_bf16_f32 v103, v196, v198
	v_cvt_pk_bf16_f32 v106, v193, v195
	v_cvt_pk_bf16_f32 v107, v191, v194
	v_cvt_pk_bf16_f32 v108, v188, v192
	v_cvt_pk_bf16_f32 v109, v187, v189
	v_cvt_pk_bf16_f32 v110, v110, v111
	v_cvt_pk_bf16_f32 v111, v112, v113
	v_cvt_pk_bf16_f32 v112, v114, v115
	v_cvt_pk_bf16_f32 v113, v116, v117
	v_cvt_pk_bf16_f32 v114, v118, v119
	v_cvt_pk_bf16_f32 v115, v120, v121
	v_cvt_pk_bf16_f32 v116, v122, v123
	v_cvt_pk_bf16_f32 v117, v124, v125
	s_add_u32 s6, s90, s6
	s_addc_u32 s7, s91, s7
	v_lshl_add_u64 v[118:119], s[6:7], 0, v[210:211]
	global_load_dwordx4 v[180:183], v[118:119], off
	ds_read_b64_tr_b16 v[118:119], v213 offset:0
	ds_read_b64_tr_b16 v[120:121], v213 offset:0x100
	ds_read_b64_tr_b16 v[122:123], v213 offset:0x1000
	ds_read_b64_tr_b16 v[124:125], v213 offset:0x1100
	ds_read_b64_tr_b16 v[126:127], v213 offset:0x2000
	ds_read_b64_tr_b16 v[128:129], v213 offset:0x2100
	ds_read_b64_tr_b16 v[188:189], v213 offset:0x3000
	ds_read_b64_tr_b16 v[190:191], v213 offset:0x3100
	s_waitcnt lgkmcnt(0)
; __device__ __forceinline__ void mask_tile(f32x16& p0, f32x16& p1, int dq, unsigned W) {
;     const float NEG = -__builtin_inff();
; #pragma unroll
;     for (int r = 0; r < 16; ++r) {
;         const int c = (r & 3) + 8 * (r >> 2);
;         if ((unsigned)(dq - c) >= W) p0[r] = NEG;
;         if ((unsigned)(dq - c - 32) >= W) p1[r] = NEG;
;     }
; }
; template <int VB, bool SK>
; __device__ __forceinline__ void pv_tile(f32x16* o, int vb0, bf16x8 pa0, bf16x8 pa1, bf16x8 pa2, bf16x8 pa3, bool act) {
;     if (SK && !act) return;
;     ...
;     PV_D0(0); PV_D0(1); PV_D0(2); PV_D0(3);
	s_nop 0
	v_mfma_f32_32x32x16_bf16 v[52:67], v[118:121], v[100:103], v[52:67]
	ds_read_b64_tr_b16 v[118:119], v213 offset:0x200
	ds_read_b64_tr_b16 v[120:121], v213 offset:0x300
	v_mfma_f32_32x32x16_bf16 v[52:67], v[122:125], v[106:109], v[52:67]
	ds_read_b64_tr_b16 v[122:123], v213 offset:0x1200
	ds_read_b64_tr_b16 v[124:125], v213 offset:0x1300
	v_mfma_f32_32x32x16_bf16 v[52:67], v[126:129], v[110:113], v[52:67]
	ds_read_b64_tr_b16 v[126:127], v213 offset:0x2200
	ds_read_b64_tr_b16 v[128:129], v213 offset:0x2300
	v_mfma_f32_32x32x16_bf16 v[52:67], v[188:191], v[114:117], v[52:67]
	ds_read_b64_tr_b16 v[188:189], v213 offset:0x3200
	ds_read_b64_tr_b16 v[190:191], v213 offset:0x3300
	s_waitcnt lgkmcnt(0)
	v_mfma_f32_32x32x16_bf16 v[36:51], v[118:121], v[100:103], v[36:51]
	ds_read_b64_tr_b16 v[118:119], v213 offset:0x400
	ds_read_b64_tr_b16 v[120:121], v213 offset:0x500
	v_mfma_f32_32x32x16_bf16 v[36:51], v[122:125], v[106:109], v[36:51]
	ds_read_b64_tr_b16 v[122:123], v213 offset:0x1400
	ds_read_b64_tr_b16 v[124:125], v213 offset:0x1500
	v_mfma_f32_32x32x16_bf16 v[36:51], v[126:129], v[110:113], v[36:51]
	ds_read_b64_tr_b16 v[126:127], v213 offset:0x2400
	ds_read_b64_tr_b16 v[128:129], v213 offset:0x2500
	v_mfma_f32_32x32x16_bf16 v[36:51], v[188:191], v[114:117], v[36:51]
	ds_read_b64_tr_b16 v[188:189], v213 offset:0x3400
	ds_read_b64_tr_b16 v[190:191], v213 offset:0x3500
	s_waitcnt lgkmcnt(0)
	v_mfma_f32_32x32x16_bf16 v[20:35], v[118:121], v[100:103], v[20:35]
	ds_read_b64_tr_b16 v[118:119], v213 offset:0x600
	ds_read_b64_tr_b16 v[120:121], v213 offset:0x700
	v_mfma_f32_32x32x16_bf16 v[20:35], v[122:125], v[106:109], v[20:35]
	ds_read_b64_tr_b16 v[122:123], v213 offset:0x1600
	ds_read_b64_tr_b16 v[124:125], v213 offset:0x1700
	v_mfma_f32_32x32x16_bf16 v[20:35], v[126:129], v[110:113], v[20:35]
	ds_read_b64_tr_b16 v[126:127], v213 offset:0x2600
	ds_read_b64_tr_b16 v[128:129], v213 offset:0x2700
	v_mfma_f32_32x32x16_bf16 v[20:35], v[188:191], v[114:117], v[20:35]
	ds_read_b64_tr_b16 v[188:189], v213 offset:0x3600
	ds_read_b64_tr_b16 v[190:191], v213 offset:0x3700
	s_waitcnt lgkmcnt(0)
	v_mfma_f32_32x32x16_bf16 v[4:19], v[118:121], v[100:103], v[4:19]
	s_cmp_le_i32 s5, s1
	s_cselect_b64 s[6:7], -1, 0
	s_cmp_gt_i32 s4, s23
	s_cselect_b64 s[4:5], -1, 0
	s_and_b64 s[4:5], s[4:5], s[6:7]
	s_and_b64 vcc, exec, s[4:5]
	v_mfma_f32_32x32x16_bf16 v[4:19], v[122:125], v[106:109], v[4:19]
	v_mfma_f32_32x32x16_bf16 v[4:19], v[126:129], v[110:113], v[4:19]
	v_mfma_f32_32x32x16_bf16 v[4:19], v[188:191], v[114:117], v[4:19]
	s_cbranch_vccnz .LBB0_372
	v_add_u32_e32 v100, 0x7b, v234
	v_cmp_gt_u32_e32 vcc, s27, v100
	v_add_u32_e32 v100, 0x5b, v234
	s_nop 0
	v_cndmask_b32_e32 v84, v2, v84, vcc
	v_cmp_gt_u32_e32 vcc, s27, v100
	v_add_u32_e32 v100, 0x7a, v234
	s_nop 0
	v_cndmask_b32_e32 v68, v2, v68, vcc
	v_cmp_gt_u32_e32 vcc, s27, v100
	v_add_u32_e32 v100, 0x5a, v234
	s_nop 0
	v_cndmask_b32_e32 v85, v2, v85, vcc
	v_cmp_gt_u32_e32 vcc, s27, v100
	v_add_u32_e32 v100, 0x79, v234
	s_nop 0
	v_cndmask_b32_e32 v69, v2, v69, vcc
	v_cmp_gt_u32_e32 vcc, s27, v100
	v_add_u32_e32 v100, 0x59, v234
	s_nop 0
	v_cndmask_b32_e32 v86, v2, v86, vcc
	v_cmp_gt_u32_e32 vcc, s27, v100
	v_add_u32_e32 v100, 0x78, v234
	s_nop 0
	v_cndmask_b32_e32 v70, v2, v70, vcc
	v_cmp_gt_u32_e32 vcc, s27, v100
	v_add_u32_e32 v100, 0x58, v234
	s_nop 0
	v_cndmask_b32_e32 v87, v2, v87, vcc
	v_cmp_gt_u32_e32 vcc, s27, v100
	v_add_u32_e32 v100, 0x73, v234
	s_nop 0
	v_cndmask_b32_e32 v71, v2, v71, vcc
	v_cmp_gt_u32_e32 vcc, s27, v100
	v_add_u32_e32 v100, 0x53, v234
	s_nop 0
	v_cndmask_b32_e32 v88, v2, v88, vcc
	v_cmp_gt_u32_e32 vcc, s27, v100
	v_add_u32_e32 v100, 0x72, v234
	s_nop 0
	v_cndmask_b32_e32 v72, v2, v72, vcc
	v_cmp_gt_u32_e32 vcc, s27, v100
	v_add_u32_e32 v100, 0x52, v234
	s_nop 0
	v_cndmask_b32_e32 v89, v2, v89, vcc
	v_cmp_gt_u32_e32 vcc, s27, v100
	v_add_u32_e32 v100, 0x71, v234
	s_nop 0
	v_cndmask_b32_e32 v73, v2, v73, vcc
	v_cmp_gt_u32_e32 vcc, s27, v100
	v_add_u32_e32 v100, 0x51, v234
	s_nop 0
	v_cndmask_b32_e32 v90, v2, v90, vcc
	v_cmp_gt_u32_e32 vcc, s27, v100
	v_add_u32_e32 v100, 0x70, v234
	s_nop 0
	v_cndmask_b32_e32 v74, v2, v74, vcc
	v_cmp_gt_u32_e32 vcc, s27, v100
	v_add_u32_e32 v100, 0x50, v234
	s_nop 0
	v_cndmask_b32_e32 v91, v2, v91, vcc
	v_cmp_gt_u32_e32 vcc, s27, v100
	v_add_u32_e32 v100, 0x6b, v234
	s_nop 0
	v_cndmask_b32_e32 v75, v2, v75, vcc
	v_cmp_gt_u32_e32 vcc, s27, v100
	v_add_u32_e32 v100, 0x4b, v234
	s_nop 0
	v_cndmask_b32_e32 v92, v2, v92, vcc
	v_cmp_gt_u32_e32 vcc, s27, v100
	v_add_u32_e32 v100, 0x6a, v234
	s_nop 0
	v_cndmask_b32_e32 v76, v2, v76, vcc
	v_cmp_gt_u32_e32 vcc, s27, v100
	v_add_u32_e32 v100, 0x4a, v234
	s_nop 0
	v_cndmask_b32_e32 v93, v2, v93, vcc
	v_cmp_gt_u32_e32 vcc, s27, v100
	v_add_u32_e32 v100, 0x69, v234
	s_nop 0
	v_cndmask_b32_e32 v77, v2, v77, vcc
	v_cmp_gt_u32_e32 vcc, s27, v100
	v_add_u32_e32 v100, 0x49, v234
	s_nop 0
	v_cndmask_b32_e32 v94, v2, v94, vcc
	v_cmp_gt_u32_e32 vcc, s27, v100
	v_add_u32_e32 v100, 0x68, v234
	s_nop 0
	v_cndmask_b32_e32 v78, v2, v78, vcc
	v_cmp_gt_u32_e32 vcc, s27, v100
	v_add_u32_e32 v100, 0x48, v234
	s_nop 0
	v_cndmask_b32_e32 v95, v2, v95, vcc
	v_cmp_gt_u32_e32 vcc, s27, v100
	v_add_u32_e32 v100, 0x63, v234
	s_nop 0
	v_cndmask_b32_e32 v79, v2, v79, vcc
	v_cmp_gt_u32_e32 vcc, s27, v100
	v_add_u32_e32 v100, 0x43, v234
	s_nop 0
	v_cndmask_b32_e32 v96, v2, v96, vcc
	v_cmp_gt_u32_e32 vcc, s27, v100
	v_add_u32_e32 v100, 0x62, v234
	s_nop 0
	v_cndmask_b32_e32 v80, v2, v80, vcc
	v_cmp_gt_u32_e32 vcc, s27, v100
	v_add_u32_e32 v100, 0x42, v234
	s_nop 0
	v_cndmask_b32_e32 v97, v2, v97, vcc
	v_cmp_gt_u32_e32 vcc, s27, v100
	v_add_u32_e32 v100, 0x61, v234
	s_nop 0
	v_cndmask_b32_e32 v81, v2, v81, vcc
	v_cmp_gt_u32_e32 vcc, s27, v100
	v_add_u32_e32 v100, 0x41, v234
	s_nop 0
	v_cndmask_b32_e32 v98, v2, v98, vcc
	v_cmp_gt_u32_e32 vcc, s27, v100
	v_add_u32_e32 v100, 0x60, v234
	s_nop 0
	v_cndmask_b32_e32 v82, v2, v82, vcc
	v_cmp_gt_u32_e32 vcc, s27, v100
	v_add_u32_e32 v100, 64, v234
	s_nop 0
	v_cndmask_b32_e32 v99, v2, v99, vcc
	v_cmp_gt_u32_e32 vcc, s27, v100
	s_nop 1
	v_cndmask_b32_e32 v83, v2, v83, vcc

; __device__ __forceinline__ void partialSM(f32x16& p0, f32x16& p1, float& m_reg, float& mn, float& alpha, const float scale) {
;     ...
;     if (__builtin_expect(__all((pmax - m_reg) * scale <= THR), 1)) { mn = m_reg; alpha = 1.f; }
;     else { mn = fmaxf(m_reg, pmax); alpha = __builtin_amdgcn_exp2f((m_reg - mn) * C2); m_reg = mn; }
;     const float mnL = -mn * C2;
;     for (int r = 0; r < 16; ++r) p0[r] = fmaf(p0[r], C2, mnL); for (int r = 0; r < 16; ++r) p1[r] = fmaf(p1[r], C2, mnL);
;     for (int r = 0; r < 16; ++r) p0[r] = __builtin_amdgcn_exp2f(p0[r]);
.LBB0_374:
	v_cndmask_b32_e64 v236, v100, v185, s[4:5]
	v_mul_f32_e32 v184, 0xbdd53b94, v236
	v_fmamk_f32 v84, v84, 0x3dd53b94, v184
	v_fmamk_f32 v85, v85, 0x3dd53b94, v184
	v_fmamk_f32 v86, v86, 0x3dd53b94, v184
	v_fmamk_f32 v87, v87, 0x3dd53b94, v184
	v_fmamk_f32 v88, v88, 0x3dd53b94, v184
	v_fmamk_f32 v89, v89, 0x3dd53b94, v184
	v_fmamk_f32 v90, v90, 0x3dd53b94, v184
	v_fmamk_f32 v91, v91, 0x3dd53b94, v184
	v_fmamk_f32 v92, v92, 0x3dd53b94, v184
	v_fmamk_f32 v93, v93, 0x3dd53b94, v184
	v_fmamk_f32 v94, v94, 0x3dd53b94, v184
	v_fmamk_f32 v95, v95, 0x3dd53b94, v184
	v_fmamk_f32 v96, v96, 0x3dd53b94, v184
	v_fmamk_f32 v97, v97, 0x3dd53b94, v184
	v_fmamk_f32 v98, v98, 0x3dd53b94, v184
	v_fmamk_f32 v99, v99, 0x3dd53b94, v184
	v_fmamk_f32 v185, v68, 0x3dd53b94, v184
	v_fmamk_f32 v186, v69, 0x3dd53b94, v184
	v_fmamk_f32 v187, v70, 0x3dd53b94, v184
	v_fmamk_f32 v188, v71, 0x3dd53b94, v184
	v_fmamk_f32 v189, v72, 0x3dd53b94, v184
	v_fmamk_f32 v190, v73, 0x3dd53b94, v184
	v_fmamk_f32 v191, v74, 0x3dd53b94, v184
	v_fmamk_f32 v192, v75, 0x3dd53b94, v184
	v_fmamk_f32 v193, v76, 0x3dd53b94, v184
	v_fmamk_f32 v194, v77, 0x3dd53b94, v184
	v_fmamk_f32 v195, v78, 0x3dd53b94, v184
	v_fmamk_f32 v196, v79, 0x3dd53b94, v184
	v_fmamk_f32 v197, v80, 0x3dd53b94, v184
	v_fmamk_f32 v198, v81, 0x3dd53b94, v184
	v_fmamk_f32 v199, v82, 0x3dd53b94, v184
	v_fmac_f32_e32 v184, 0x3dd53b94, v83
	v_exp_f32_e32 v68, v84
	v_exp_f32_e32 v69, v85
	v_exp_f32_e32 v70, v86
	v_exp_f32_e32 v71, v87
	v_exp_f32_e32 v72, v88
	v_exp_f32_e32 v73, v89
	v_exp_f32_e32 v74, v90
	v_exp_f32_e32 v75, v91
	v_exp_f32_e32 v76, v92
	v_exp_f32_e32 v77, v93
	v_exp_f32_e32 v78, v94
	v_exp_f32_e32 v79, v95
	v_exp_f32_e32 v80, v96
	v_exp_f32_e32 v81, v97
	v_exp_f32_e32 v82, v98
	v_exp_f32_e32 v83, v99
	s_waitcnt lgkmcnt(0)
	s_barrier
	s_add_i32 s4, s52, 1
	s_cmp_lt_u32 s4, s21
	s_cselect_b64 s[6:7], -1, 0
	s_cmp_ge_u32 s4, s21
	s_cbranch_scc1 .Lmla_ld2_done
	s_mov_b32 s25, s45
	s_lshl_b64 s[4:5], s[24:25], 7
	s_add_u32 s54, s86, s4
	s_addc_u32 s55, s87, s5
	s_add_u32 s4, s88, s4
	s_addc_u32 s5, s89, s5
	v_lshl_add_u64 v[164:165], s[4:5], 0, v[200:201]
	v_add_co_u32_e32 v168, vcc, s43, v164
	s_lshl_b64 s[4:5], s[24:25], 6
	s_nop 0
	v_addc_co_u32_e32 v169, vcc, 0, v165, vcc
	v_lshl_add_u64 v[172:173], s[54:55], 0, v[200:201]
	s_add_u32 s4, s90, s4
	v_add_co_u32_e32 v176, vcc, 0x2000, v172
	s_addc_u32 s5, s91, s5
	s_nop 0
	v_addc_co_u32_e32 v177, vcc, 0, v173, vcc
	v_lshl_add_u64 v[180:181], s[4:5], 0, v[210:211]
	global_load_dwordx4 v[164:167], v[164:165], off
	s_nop 0
	global_load_dwordx4 v[168:171], v[168:169], off
	s_nop 0
	global_load_dwordx4 v[172:175], v[172:173], off
	s_nop 0
	global_load_dwordx4 v[176:179], v[176:177], off
	s_nop 0
	global_load_dwordx4 v[180:183], v[180:181], off
; #define PK4(P, B_, OUT) do { const u32x4 w = {cvtpk(P[B_+0], P[B_+1]), cvtpk(P[B_+2], P[B_+3]), cvtpk(P[B_+4], P[B_+5]), cvtpk(P[B_+6], P[B_+7])};     \
;         OUT = *reinterpret_cast<const bf16x8*>(&w); } while (0)
; __device__ __forceinline__ void finishSM(f32x16& p0, f32x16& p1, float alpha, float& l_reg, bf16x8& pa0, bf16x8& pa1, bf16x8& pa2, bf16x8& pa3) {
;     for (int r = 0; r < 16; ++r) p1[r] = __builtin_amdgcn_exp2f(p1[r]);
;     float ps = 0; for (int r = 0; r < 16; ++r) ps += p0[r]; for (int r = 0; r < 16; ++r) ps += p1[r];
;     { auto rr = __builtin_amdgcn_permlane32_swap(__float_as_uint(ps), __float_as_uint(ps), false, false);
;       ps = __uint_as_float(rr[0]) + __uint_as_float(rr[1]); }
;     l_reg = l_reg * alpha + ps;
;     ...
;     PK4(p0, 0, pa0); PK4(p0, 8, pa1); PK4(p1, 0, pa2); PK4(p1, 8, pa3);
;     ...
; }
; template <int KB, bool SK, bool PE>
; __device__ __forceinline__ void qkt(f32x16& p0, f32x16& p1, const char* lds, int r32, int hi, int wid, int lane, const bf16x8* qr, bool act) {
;     if (SK && !act) { const float NEG = -__builtin_inff();
; #pragma unroll
;         for (int r = 0; r < 16; ++r) { p0[r] = NEG; p1[r] = NEG; } return; }
;     p0 = f32x16{}; p1 = f32x16{};
;     const char* kb[4];
; #pragma unroll
;     for (int dd = 0; dd < 4; ++dd) kb[dd] = lds + OFF_K + KB * SHM_K + KSWZ(r32, (dd * 16 + hi * 8) * 2);
; #pragma unroll
;     for (int d0 = 0; d0 < 8; ++d0) { const char* a = kb[d0 & 3] + (d0 >> 2) * 128;
;         bf16x8 b0 = *reinterpret_cast<const bf16x8*>(a);
;         bf16x8 b1 = *reinterpret_cast<const bf16x8*>(a + 32 * 256);
;         p0 = __builtin_amdgcn_mfma_f32_32x32x16_bf16(b0, qr[d0], p0, 0, 0, 0);
;         p1 = __builtin_amdgcn_mfma_f32_32x32x16_bf16(b1, qr[d0], p1, 0, 0, 0); }
;     if constexpr (PE) {
;         const char* kp = lds + OFF_KPE + KB * SHM_KPE + r32 * KPE_ROW + hi * 16;
;         const char* qp = lds + OFF_QPE + wid * 4096 + lane * 16;
; #pragma unroll
;         for (int d0 = 0; d0 < 4; ++d0) {
;             bf16x8 b0 = *reinterpret_cast<const bf16x8*>(kp + d0 * 32);
;             bf16x8 b1 = *reinterpret_cast<const bf16x8*>(kp + d0 * 32 + 32 * KPE_ROW);
;             bf16x8 qf = *reinterpret_cast<const bf16x8*>(qp + d0 * 1024);
;             p0 = __builtin_amdgcn_mfma_f32_32x32x16_bf16(b0, qf, p0, 0, 0, 0);
;             p1 = __builtin_amdgcn_mfma_f32_32x32x16_bf16(b1, qf, p1, 0, 0, 0); }
;     }
.Lmla_ld2_done:
	ds_read_b128 v[84:87], v222 offset:32768
	ds_read_b128 v[88:91], v222 offset:40960
	s_waitcnt lgkmcnt(1)
	v_mfma_f32_32x32x16_bf16 v[116:131], v[84:87], v[160:163], 0
	s_waitcnt lgkmcnt(0)
	v_mfma_f32_32x32x16_bf16 v[100:115], v[88:91], v[160:163], 0
	ds_read_b128 v[84:87], v221 offset:32768
	ds_read_b128 v[88:91], v221 offset:40960
	s_waitcnt lgkmcnt(1)
	v_mfma_f32_32x32x16_bf16 v[116:131], v[84:87], v[156:159], v[116:131]
	s_waitcnt lgkmcnt(0)
	v_mfma_f32_32x32x16_bf16 v[100:115], v[88:91], v[156:159], v[100:115]
	ds_read_b128 v[84:87], v220 offset:32768
	ds_read_b128 v[88:91], v220 offset:40960
	s_waitcnt lgkmcnt(1)
	v_mfma_f32_32x32x16_bf16 v[116:131], v[84:87], v[152:155], v[116:131]
	s_waitcnt lgkmcnt(0)
	v_mfma_f32_32x32x16_bf16 v[100:115], v[88:91], v[152:155], v[100:115]
	ds_read_b128 v[84:87], v219 offset:32768
	ds_read_b128 v[88:91], v219 offset:40960
	s_waitcnt lgkmcnt(1)
	v_mfma_f32_32x32x16_bf16 v[116:131], v[84:87], v[148:151], v[116:131]
	s_waitcnt lgkmcnt(0)
	v_mfma_f32_32x32x16_bf16 v[100:115], v[88:91], v[148:151], v[100:115]
	ds_read_b128 v[84:87], v222 offset:32896
	ds_read_b128 v[88:91], v222 offset:41088
	s_waitcnt lgkmcnt(1)
	v_mfma_f32_32x32x16_bf16 v[116:131], v[84:87], v[144:147], v[116:131]
	s_waitcnt lgkmcnt(0)
	v_mfma_f32_32x32x16_bf16 v[100:115], v[88:91], v[144:147], v[100:115]
	ds_read_b128 v[84:87], v221 offset:32896
	ds_read_b128 v[88:91], v221 offset:41088
	s_waitcnt lgkmcnt(1)
	v_mfma_f32_32x32x16_bf16 v[116:131], v[84:87], v[140:143], v[116:131]
	s_waitcnt lgkmcnt(0)
	v_mfma_f32_32x32x16_bf16 v[100:115], v[88:91], v[140:143], v[100:115]
	ds_read_b128 v[84:87], v220 offset:32896
	ds_read_b128 v[88:91], v220 offset:41088
	s_waitcnt lgkmcnt(1)
	v_mfma_f32_32x32x16_bf16 v[116:131], v[84:87], v[136:139], v[116:131]
	s_waitcnt lgkmcnt(0)
	v_mfma_f32_32x32x16_bf16 v[100:115], v[88:91], v[136:139], v[100:115]
	ds_read_b128 v[84:87], v219 offset:32896
	ds_read_b128 v[88:91], v219 offset:41088
	s_waitcnt lgkmcnt(1)
	v_mfma_f32_32x32x16_bf16 v[116:131], v[84:87], v[132:135], v[116:131]
	s_waitcnt lgkmcnt(0)
	v_mfma_f32_32x32x16_bf16 v[100:115], v[88:91], v[132:135], v[100:115]
	ds_read_b128 v[84:87], v232 offset:4608
	ds_read_b128 v[88:91], v215
	ds_read_b128 v[92:95], v232
	ds_read_b128 v[96:99], v232 offset:32
	s_waitcnt lgkmcnt(1)
	v_mfma_f32_32x32x16_bf16 v[116:131], v[92:95], v[88:91], v[116:131]
	v_mfma_f32_32x32x16_bf16 v[100:115], v[84:87], v[88:91], v[100:115]
	ds_read_b128 v[84:87], v232 offset:4640
	ds_read_b128 v[88:91], v215 offset:1024
	s_waitcnt lgkmcnt(0)
	v_mfma_f32_32x32x16_bf16 v[116:131], v[96:99], v[88:91], v[116:131]
	v_exp_f32_e32 v99, v184
	v_add_f32_e32 v184, 0, v68
	v_add_f32_e32 v184, v69, v184
	v_add_f32_e32 v184, v70, v184
	v_add_f32_e32 v184, v71, v184
	v_add_f32_e32 v184, v72, v184
	v_add_f32_e32 v184, v73, v184
	v_mfma_f32_32x32x16_bf16 v[100:115], v[84:87], v[88:91], v[100:115]
	ds_read_b128 v[84:87], v232 offset:64
	ds_read_b128 v[88:91], v232 offset:4672
	ds_read_b128 v[92:95], v215 offset:2048
	v_add_f32_e32 v184, v74, v184
	v_add_f32_e32 v184, v75, v184
	v_add_f32_e32 v184, v76, v184
	v_add_f32_e32 v184, v77, v184
	v_add_f32_e32 v184, v78, v184
	v_add_f32_e32 v184, v79, v184
	s_waitcnt lgkmcnt(0)
	v_mfma_f32_32x32x16_bf16 v[116:131], v[84:87], v[92:95], v[116:131]
	v_add_f32_e32 v184, v80, v184
	v_add_f32_e32 v184, v81, v184
	v_add_f32_e32 v184, v82, v184
	v_add_f32_e32 v184, v83, v184
	v_exp_f32_e32 v96, v197
	v_exp_f32_e32 v97, v198
	v_exp_f32_e32 v98, v199
	v_mfma_f32_32x32x16_bf16 v[100:115], v[88:91], v[92:95], v[100:115]
	ds_read_b128 v[84:87], v232 offset:96
	ds_read_b128 v[88:91], v232 offset:4704
	ds_read_b128 v[92:95], v215 offset:3072
	s_waitcnt lgkmcnt(0)
	v_mfma_f32_32x32x16_bf16 v[116:131], v[84:87], v[92:95], v[116:131]
	v_exp_f32_e32 v84, v185
	v_exp_f32_e32 v85, v186
	v_exp_f32_e32 v86, v187
	v_exp_f32_e32 v87, v188
	v_add_f32_e32 v184, v84, v184
	v_add_f32_e32 v184, v85, v184
	v_add_f32_e32 v184, v86, v184
	v_mfma_f32_32x32x16_bf16 v[100:115], v[88:91], v[92:95], v[100:115]
	v_exp_f32_e32 v88, v189
	v_exp_f32_e32 v89, v190
	v_exp_f32_e32 v90, v191
	v_exp_f32_e32 v91, v192
	v_add_f32_e32 v184, v87, v184
	v_exp_f32_e32 v92, v193
	v_add_f32_e32 v184, v88, v184
	v_exp_f32_e32 v93, v194
	v_add_f32_e32 v184, v89, v184
	v_exp_f32_e32 v94, v195
	v_add_f32_e32 v184, v90, v184
	v_exp_f32_e32 v95, v196
	v_add_f32_e32 v184, v91, v184
	v_add_f32_e32 v184, v92, v184
	v_add_f32_e32 v184, v93, v184
	v_add_f32_e32 v184, v94, v184
	v_add_f32_e32 v184, v95, v184
	v_add_f32_e32 v184, v96, v184
	v_add_f32_e32 v184, v97, v184
	v_add_f32_e32 v184, v98, v184
	v_add_f32_e32 v238, v99, v184
	v_mov_b32_e32 v239, v238
	s_nop 1
	v_permlane32_swap_b32_e32 v238, v239
	v_cvt_pk_bf16_f32 v184, v68, v69
	v_cvt_pk_bf16_f32 v185, v70, v71
	v_cvt_pk_bf16_f32 v186, v72, v73
	v_cvt_pk_bf16_f32 v187, v74, v75
	v_cvt_pk_bf16_f32 v192, v76, v77
	v_cvt_pk_bf16_f32 v193, v78, v79
	v_cvt_pk_bf16_f32 v194, v80, v81
	v_cvt_pk_bf16_f32 v195, v82, v83
	v_cvt_pk_bf16_f32 v196, v84, v85
	v_cvt_pk_bf16_f32 v197, v86, v87
	v_cvt_pk_bf16_f32 v198, v88, v89
	v_cvt_pk_bf16_f32 v199, v90, v91
	v_cvt_pk_bf16_f32 v188, v92, v93
	v_cvt_pk_bf16_f32 v189, v94, v95
	v_cvt_pk_bf16_f32 v190, v96, v97
	v_cvt_pk_bf16_f32 v191, v98, v99
